# P5 sample rows handled by wave 0 of workgroups 0..127 instead of all 8 waves of workgroups 0..15 (same tail rebalancing as P8)
# baseline (speedup 1.0000x reference)
; template <int ph>
; __device__ __forceinline__ void run_phase(const Args& args, LAS unsigned char* lds, const int G, const int bx, const bool fin = true) {
;     ...
;         for (int row = gw; row < MT; row += ngw) {
;             const bool smp = row >= MP; const int t = row & (T - 1), b = row >> 11, si = row - MP;
.LBB0_682:
	s_add_i32 s0, s0, s10
	s_add_i32 s46, s46, s10
	s_cmpk_lt_i32 s0, 0x4000
	s_cbranch_scc1 .Lp5_noremap
	s_add_i32 s98, s0, 0xffffc000
	s_and_b32 s99, s98, 7
	s_lshr_b32 s98, s98, 3
	s_cmp_eq_u32 s99, 0
	s_cselect_b32 s98, s98, 0x80
	s_add_i32 s0, s98, 0x4000
	s_mov_b32 s46, s98
.Lp5_noremap:
	s_cmpk_lt_i32 s0, 0x4080
	v_lshl_add_u64 v[62:63], v[62:63], 0, s[20:21]
	s_cbranch_scc0 .LBB0_707
